# v33 + Fourier pre-pass Nyquist-row dot loop: next 16-byte piece loaded one iteration ahead (prefetch rotation)
# speedup vs baseline: 1.0072x; 1.0072x over previous
; __global__ void __launch_bounds__(512, 2) mk_fwd(Args a) {
;     ...
;                       const int gt = vcu * 512 + tid;
;                       if (gt < NB * DM) { const int b = gt >> 10, ch = gt & 1023, g = ch >> 8, m = ch & 255; const bf16_t* xr = XB + ((size_t)b * SEQ + 2048) * DM + g * 256; float acc_ = 0.f;
;                           for (int c = 0; c < 256; ++c) acc_ += bf2f(xr[c]) * __builtin_amdgcn_cosf((float)((m * c) & 255) * (1.0f / 256.0f));
;                           ((float*)(ws + WS_YCH))[gt] = acc_; }
.Lfold_done:
.LBB0_603:
	v_add_u32_e32 v3, s73, v0
	v_readlane_b32 s2, v252, 4
	s_nop 1
	v_add_u32_e32 v2, s2, v3
	v_cmp_gt_i32_e32 vcc, s88, v2
	s_and_saveexec_b64 s[4:5], vcc
	s_cbranch_execz .LBB0_607
	v_readlane_b32 s2, v253, 30
	v_ashrrev_i32_e32 v4, 10, v2
	v_ashrrev_i32_e32 v5, 31, v4
	v_lshl_add_u32 v12, v0, 3, s2
	v_readlane_b32 s2, v253, 50
	v_lshlrev_b64 v[10:11], 23, v[4:5]
	s_nop 0
	v_lshl_add_u32 v13, v0, 1, s2
	v_readlane_b32 s2, v254, 1
	s_nop 1
	v_mov_b32_e32 v4, s2
	v_mad_u64_u32 v[4:5], s[8:9], v0, 3, v[4:5]
	v_readlane_b32 s2, v253, 51
	s_nop 1
	v_lshl_add_u32 v5, v0, 2, s2
	v_readlane_b32 s2, v254, 2
	s_nop 1
	v_mov_b32_e32 v6, s2
	v_readlane_b32 s2, v254, 3
	v_mad_u64_u32 v[6:7], s[8:9], v0, 5, v[6:7]
	s_nop 0
	v_mov_b32_e32 v8, s2
	v_readlane_b32 s2, v254, 4
	v_mad_u64_u32 v[8:9], s[8:9], v0, 6, v[8:9]
	s_nop 0
	v_mov_b32_e32 v14, s2
	v_mad_u64_u32 v[0:1], s[8:9], v0, 7, v[14:15]
	v_lshlrev_b32_e32 v1, 1, v2
	v_and_or_b32 v10, v1, s11, v10
	v_lshl_add_u64 v[10:11], s[0:1], 0, v[10:11]
	v_mov_b32_e32 v1, 0
	s_mov_b64 s[8:9], 0
	v_mov_b32_e32 v7, 0
	v_lshl_add_u64 v[26:27], v[10:11], 0, s[8:9]
	v_add_co_u32_e32 v26, vcc, 0x5e00000, v26
	s_nop 1
	v_addc_co_u32_e32 v27, vcc, 0, v27, vcc
	global_load_dwordx4 v[22:25], v[26:27], off
.LBB0_605:
	v_and_b32_e32 v18, 0xf8, v7
	v_cvt_f32_ubyte0_e32 v18, v18
	v_mul_f32_e32 v18, 0x3b800000, v18
	v_cos_f32_e32 v18, v18
	s_add_u32 s8, s8, 16
	s_addc_u32 s9, s9, 0
	s_waitcnt vmcnt(0)
	v_mov_b32_e32 v14, v22
	v_mov_b32_e32 v15, v23
	v_mov_b32_e32 v16, v24
	v_mov_b32_e32 v17, v25
	v_lshl_add_u64 v[26:27], v[10:11], 0, s[8:9]
	v_add_co_u32_e32 v26, vcc, 0x5e00000, v26
	s_nop 1
	v_addc_co_u32_e32 v27, vcc, 0, v27, vcc
	global_load_dwordx4 v[22:25], v[26:27], off
	s_cmpk_eq_i32 s8, 0x200
	v_lshlrev_b32_e32 v9, 16, v14
	v_fmac_f32_e32 v1, v18, v9
	v_and_b32_e32 v9, 0xffff0000, v14
	v_add_u32_e32 v14, v3, v7
	v_cvt_f32_ubyte0_e32 v14, v14
	v_mul_f32_e32 v14, 0x3b800000, v14
	v_cos_f32_e32 v14, v14
	s_nop 0
	v_fmac_f32_e32 v1, v14, v9
	v_add_u32_e32 v14, v13, v7
	v_and_b32_e32 v14, 0xfe, v14
	v_cvt_f32_ubyte0_e32 v14, v14
	v_mul_f32_e32 v14, 0x3b800000, v14
	v_cos_f32_e32 v14, v14
	v_lshlrev_b32_e32 v9, 16, v15
	v_fmac_f32_e32 v1, v14, v9
	v_add_u32_e32 v14, v4, v7
	v_cvt_f32_ubyte0_e32 v14, v14
	v_mul_f32_e32 v14, 0x3b800000, v14
	v_cos_f32_e32 v14, v14
	v_and_b32_e32 v9, 0xffff0000, v15
	v_fmac_f32_e32 v1, v14, v9
	v_add_u32_e32 v14, v5, v7
	v_and_b32_e32 v14, 0xfc, v14
	v_cvt_f32_ubyte0_e32 v14, v14
	v_mul_f32_e32 v14, 0x3b800000, v14
	v_cos_f32_e32 v14, v14
	v_lshlrev_b32_e32 v9, 16, v16
	v_fmac_f32_e32 v1, v14, v9
	v_add_u32_e32 v14, v6, v7
	v_cvt_f32_ubyte0_e32 v14, v14
	v_mul_f32_e32 v14, 0x3b800000, v14
	v_cos_f32_e32 v14, v14
	v_and_b32_e32 v9, 0xffff0000, v16
	v_fmac_f32_e32 v1, v14, v9
	v_add_u32_e32 v14, v8, v7
	v_and_b32_e32 v14, 0xfe, v14
	v_cvt_f32_ubyte0_e32 v14, v14
	v_mul_f32_e32 v14, 0x3b800000, v14
	v_cos_f32_e32 v14, v14
	v_lshlrev_b32_e32 v9, 16, v17
	v_fmac_f32_e32 v1, v14, v9
	v_add_u32_e32 v14, v0, v7
	v_cvt_f32_ubyte0_e32 v14, v14
	v_mul_f32_e32 v14, 0x3b800000, v14
	v_cos_f32_e32 v14, v14
	v_and_b32_e32 v9, 0xffff0000, v17
	v_add_u32_e32 v7, v7, v12
	v_fmac_f32_e32 v1, v14, v9
	s_cbranch_scc0 .LBB0_605
	v_ashrrev_i32_e32 v3, 31, v2
	v_lshl_add_u64 v[2:3], v[2:3], 2, s[0:1]
	v_add_co_u32_e32 v2, vcc, 0x5880000, v2
	s_nop 1
	v_addc_co_u32_e32 v3, vcc, 0, v3, vcc
	flat_store_dword v[2:3], v1
